# nt streaming hint also on P1's 80 one-pass f32 weight-transpose loads (on top of the P0 nt loads); P10 loads left cached (nt there was slower)
# speedup vs baseline: 1.0104x; 1.0013x over previous
; __device__ __forceinline__ void transpose_item(const float* W, int K, int N, int c0, int ncols, bf16_t* WT, int row_off, float scale, LAS float* scr, int item, int lane) {
;     ...
; #pragma unroll 8
;     for (int i = 0; i < 32; ++i) { const int kk = 2 * i + (lane >> 5); scr[kk * 33 + (lane & 31)] = W[(size_t)(k0 + kk) * N + c0 + n0 + (lane & 31)] * scale; }
;     asm volatile("s_waitcnt lgkmcnt(0)" ::: "memory");
.LBB0_230:
	s_lshl_b32 s34, s0, 1
	s_lshl_b32 s35, s5, 1
	v_or_b32_e32 v36, s35, v2
	s_add_i32 s36, s34, 4
	s_add_i32 s37, s35, 4
	s_add_i32 s38, s34, 8
	s_add_i32 s39, s35, 8
	s_add_i32 s40, s34, 12
	s_add_i32 s41, s35, 12
	s_add_i32 s42, s34, 16
	s_add_i32 s43, s35, 16
	s_add_i32 s44, s34, 20
	s_add_i32 s45, s35, 20
	s_add_i32 s46, s34, 24
	s_add_i32 s47, s35, 24
	s_add_i32 s48, s34, 28
	s_add_i32 s49, s35, 28
	v_or_b32_e32 v34, s34, v5
	v_ashrrev_i32_e32 v37, 31, v36
	v_or_b32_e32 v38, s36, v5
	v_or_b32_e32 v40, s37, v2
	v_or_b32_e32 v42, s38, v5
	v_or_b32_e32 v44, s39, v2
	v_or_b32_e32 v46, s40, v5
	v_or_b32_e32 v48, s41, v2
	v_or_b32_e32 v50, s42, v5
	v_or_b32_e32 v52, s43, v2
	v_or_b32_e32 v54, s44, v5
	v_or_b32_e32 v56, s45, v2
	v_or_b32_e32 v58, s46, v5
	v_or_b32_e32 v60, s47, v2
	v_or_b32_e32 v62, s48, v5
	v_or_b32_e32 v64, s49, v2
	v_ashrrev_i32_e32 v35, 31, v34
	v_lshlrev_b64 v[36:37], 12, v[36:37]
	v_ashrrev_i32_e32 v41, 31, v40
	v_ashrrev_i32_e32 v39, 31, v38
	v_ashrrev_i32_e32 v45, 31, v44
	v_ashrrev_i32_e32 v43, 31, v42
	v_ashrrev_i32_e32 v49, 31, v48
	v_ashrrev_i32_e32 v47, 31, v46
	v_ashrrev_i32_e32 v53, 31, v52
	v_ashrrev_i32_e32 v51, 31, v50
	v_ashrrev_i32_e32 v57, 31, v56
	v_ashrrev_i32_e32 v55, 31, v54
	v_ashrrev_i32_e32 v61, 31, v60
	v_ashrrev_i32_e32 v59, 31, v58
	v_ashrrev_i32_e32 v65, 31, v64
	v_ashrrev_i32_e32 v63, 31, v62
	v_lshlrev_b64 v[34:35], 12, v[34:35]
	v_lshl_add_u64 v[36:37], v[26:27], 0, v[36:37]
	v_lshlrev_b64 v[38:39], 12, v[38:39]
	v_lshlrev_b64 v[40:41], 12, v[40:41]
	v_lshlrev_b64 v[42:43], 12, v[42:43]
	v_lshlrev_b64 v[44:45], 12, v[44:45]
	v_lshlrev_b64 v[46:47], 12, v[46:47]
	v_lshlrev_b64 v[48:49], 12, v[48:49]
	v_lshlrev_b64 v[50:51], 12, v[50:51]
	v_lshlrev_b64 v[52:53], 12, v[52:53]
	v_lshlrev_b64 v[54:55], 12, v[54:55]
	v_lshlrev_b64 v[56:57], 12, v[56:57]
	v_lshlrev_b64 v[58:59], 12, v[58:59]
	v_lshlrev_b64 v[60:61], 12, v[60:61]
	v_lshlrev_b64 v[62:63], 12, v[62:63]
	v_lshlrev_b64 v[64:65], 12, v[64:65]
	v_lshl_add_u64 v[34:35], v[26:27], 0, v[34:35]
	v_lshl_add_u64 v[40:41], v[26:27], 0, v[40:41]
	v_lshl_add_u64 v[38:39], v[26:27], 0, v[38:39]
	v_lshl_add_u64 v[44:45], v[26:27], 0, v[44:45]
	v_lshl_add_u64 v[42:43], v[26:27], 0, v[42:43]
	v_lshl_add_u64 v[48:49], v[26:27], 0, v[48:49]
	v_lshl_add_u64 v[46:47], v[26:27], 0, v[46:47]
	v_lshl_add_u64 v[52:53], v[26:27], 0, v[52:53]
	v_lshl_add_u64 v[50:51], v[26:27], 0, v[50:51]
	v_lshl_add_u64 v[56:57], v[26:27], 0, v[56:57]
	v_lshl_add_u64 v[54:55], v[26:27], 0, v[54:55]
	v_lshl_add_u64 v[60:61], v[26:27], 0, v[60:61]
	v_lshl_add_u64 v[58:59], v[26:27], 0, v[58:59]
	v_lshl_add_u64 v[64:65], v[26:27], 0, v[64:65]
	v_lshl_add_u64 v[62:63], v[26:27], 0, v[62:63]
	global_load_dword v25, v[36:37], off nt
	global_load_dword v28, v[34:35], off nt
	global_load_dword v66, v[40:41], off nt
	global_load_dword v67, v[38:39], off nt
	global_load_dword v68, v[44:45], off nt
	global_load_dword v69, v[42:43], off nt
	global_load_dword v70, v[48:49], off nt
	global_load_dword v71, v[46:47], off nt
	global_load_dword v72, v[52:53], off nt
	global_load_dword v73, v[50:51], off nt
	global_load_dword v74, v[56:57], off nt
	global_load_dword v75, v[54:55], off nt
	global_load_dword v76, v[60:61], off nt
	global_load_dword v77, v[58:59], off nt
	global_load_dword v78, v[64:65], off nt
	global_load_dword v79, v[62:63], off nt
	v_or_b32_e32 v36, s34, v1
	v_or_b32_e32 v34, s35, v0
	s_add_i32 s5, s5, 16
	s_add_i32 s0, s0, 16
	s_add_i32 s29, s29, -16
	v_mad_u64_u32 v[34:35], s[34:35], v34, s31, v[4:5]
	v_mad_u64_u32 v[36:37], s[34:35], v36, s31, v[4:5]
	v_or_b32_e32 v35, s36, v1
	v_or_b32_e32 v37, s37, v0
	v_or_b32_e32 v44, s38, v1
	v_or_b32_e32 v42, s39, v0
	v_or_b32_e32 v48, s40, v1
	v_or_b32_e32 v46, s41, v0
	v_or_b32_e32 v52, s42, v1
	v_or_b32_e32 v50, s43, v0
	v_or_b32_e32 v56, s44, v1
	v_or_b32_e32 v54, s45, v0
	v_or_b32_e32 v60, s46, v1
	v_or_b32_e32 v58, s47, v0
	v_or_b32_e32 v64, s48, v1
	v_or_b32_e32 v62, s49, v0
	s_cmp_lg_u32 s29, 0
	v_mad_u64_u32 v[38:39], s[34:35], v37, s31, v[4:5]
	v_mad_u64_u32 v[40:41], s[34:35], v35, s31, v[4:5]
	v_mad_u64_u32 v[42:43], s[34:35], v42, s31, v[4:5]
	v_mad_u64_u32 v[44:45], s[34:35], v44, s31, v[4:5]
	v_mad_u64_u32 v[46:47], s[34:35], v46, s31, v[4:5]
	v_mad_u64_u32 v[48:49], s[34:35], v48, s31, v[4:5]
	v_mad_u64_u32 v[50:51], s[34:35], v50, s31, v[4:5]
	v_mad_u64_u32 v[52:53], s[34:35], v52, s31, v[4:5]
	v_mad_u64_u32 v[54:55], s[34:35], v54, s31, v[4:5]
	v_mad_u64_u32 v[56:57], s[34:35], v56, s31, v[4:5]
	v_mad_u64_u32 v[58:59], s[34:35], v58, s31, v[4:5]
	v_mad_u64_u32 v[60:61], s[34:35], v60, s31, v[4:5]
	v_mad_u64_u32 v[62:63], s[34:35], v62, s31, v[4:5]
	v_mad_u64_u32 v[64:65], s[34:35], v64, s31, v[4:5]
	s_waitcnt vmcnt(0)
	ds_write_b32 v34, v25
	ds_write_b32 v36, v28
	ds_write_b32 v38, v66
	ds_write_b32 v40, v67
	ds_write_b32 v42, v68
	ds_write_b32 v44, v69
	ds_write_b32 v46, v70
	ds_write_b32 v48, v71
	ds_write_b32 v50, v72
	ds_write_b32 v52, v73
	ds_write_b32 v54, v74
	ds_write_b32 v56, v75
	ds_write_b32 v58, v76
	ds_write_b32 v60, v77
	ds_write_b32 v62, v78
	ds_write_b32 v64, v79
	s_cbranch_scc1 .LBB0_230
; #define LAS __attribute__((address_space(3)))
; __device__ __forceinline__ unsigned cvtpk(float lo, float hi) { return pg8::cvt_pk_bf16(lo, hi); }
; __device__ __forceinline__ void transpose_item(const float* W, int K, int N, int c0, int ncols, bf16_t* WT, int row_off, float scale, LAS float* scr, int item, int lane) {
;     ...
;     const int c = lane & 7;
; #pragma unroll
;     for (int j = 0; j < 4; ++j) { const int n = (lane >> 3) + 8 * j; const LAS float* s = scr + (8 * c) * 33 + n;
;         u32x4 o; o.x = cvtpk(s[0 * 33], s[1 * 33]); o.y = cvtpk(s[2 * 33], s[3 * 33]); o.z = cvtpk(s[4 * 33], s[5 * 33]); o.w = cvtpk(s[6 * 33], s[7 * 33]);
;         *(u32x4*)(WT + (size_t)(row_off + n0 + n) * K + k0 + 8 * c) = o; }
;     asm volatile("s_waitcnt lgkmcnt(0)" ::: "memory");
	s_waitcnt lgkmcnt(0)
	ds_read2_b32 v[26:27], v30 offset0:33 offset1:41
	ds_read2_b32 v[38:39], v30 offset1:8
	ds_read2_b32 v[40:41], v30 offset0:66 offset1:74
	ds_read2_b32 v[42:43], v30 offset0:99 offset1:107
	ds_read2_b32 v[44:45], v30 offset0:132 offset1:140
	ds_read2_b32 v[46:47], v30 offset0:165 offset1:173
	ds_read2_b32 v[48:49], v30 offset0:198 offset1:206
	ds_read2_b32 v[50:51], v30 offset0:231 offset1:239
	v_or_b32_e32 v54, s4, v29
	s_ashr_i32 s29, s28, 31
	v_ashrrev_i32_e32 v55, 31, v54
	v_lshl_add_u64 v[52:53], s[28:29], 1, v[14:15]
	v_lshlrev_b64 v[54:55], 11, v[54:55]
	s_waitcnt lgkmcnt(6)
	v_cvt_pk_bf16_f32 v34, v38, v26
	s_waitcnt lgkmcnt(4)
	v_cvt_pk_bf16_f32 v35, v40, v42
	s_waitcnt lgkmcnt(2)
	v_cvt_pk_bf16_f32 v36, v44, v46
	s_waitcnt lgkmcnt(0)
	v_cvt_pk_bf16_f32 v37, v48, v50
	v_lshl_add_u64 v[54:55], v[52:53], 0, v[54:55]
	v_or_b32_e32 v26, s4, v31
	global_store_dwordx4 v[54:55], v[34:37], off
	s_nop 1
	v_cvt_pk_bf16_f32 v34, v39, v27
	v_ashrrev_i32_e32 v27, 31, v26
	v_cvt_pk_bf16_f32 v35, v41, v43
	v_cvt_pk_bf16_f32 v36, v45, v47
	v_cvt_pk_bf16_f32 v37, v49, v51
	v_lshlrev_b64 v[26:27], 11, v[26:27]
	ds_read2_b32 v[38:39], v30 offset0:49 offset1:57
	ds_read2_b32 v[40:41], v30 offset0:16 offset1:24
	ds_read2_b32 v[42:43], v30 offset0:82 offset1:90
	ds_read2_b32 v[44:45], v30 offset0:115 offset1:123
	ds_read2_b32 v[46:47], v30 offset0:148 offset1:156
	ds_read2_b32 v[48:49], v30 offset0:181 offset1:189
	ds_read2_b32 v[50:51], v30 offset0:214 offset1:222
	ds_read2_b32 v[54:55], v30 offset0:247 offset1:255
	v_lshl_add_u64 v[26:27], v[52:53], 0, v[26:27]
	global_store_dwordx4 v[26:27], v[34:37], off
	v_or_b32_e32 v26, s4, v32
	v_ashrrev_i32_e32 v27, 31, v26
	v_lshlrev_b64 v[26:27], 11, v[26:27]
	s_waitcnt lgkmcnt(6)
	v_cvt_pk_bf16_f32 v34, v40, v38
	s_waitcnt lgkmcnt(4)
	v_cvt_pk_bf16_f32 v35, v42, v44
	s_waitcnt lgkmcnt(2)
	v_cvt_pk_bf16_f32 v36, v46, v48
	s_waitcnt lgkmcnt(0)
	v_cvt_pk_bf16_f32 v37, v50, v54
	v_lshl_add_u64 v[26:27], v[52:53], 0, v[26:27]
	global_store_dwordx4 v[26:27], v[34:37], off
	v_or_b32_e32 v26, s4, v33
	v_ashrrev_i32_e32 v27, 31, v26
	v_lshlrev_b64 v[26:27], 11, v[26:27]
	v_cvt_pk_bf16_f32 v34, v41, v39
	v_cvt_pk_bf16_f32 v35, v43, v45
	v_cvt_pk_bf16_f32 v36, v47, v49
	v_cvt_pk_bf16_f32 v37, v51, v55
	v_lshl_add_u64 v[26:27], v[52:53], 0, v[26:27]
	global_store_dwordx4 v[26:27], v[34:37], off
	s_waitcnt lgkmcnt(0)
	s_mov_b32 s34, s11

; __device__ __forceinline__ void transpose_item(const float* W, int K, int N, int c0, int ncols, bf16_t* WT, int row_off, float scale, LAS float* scr, int item, int lane) {
;     ...
; #pragma unroll 8
;     for (int i = 0; i < 32; ++i) { const int kk = 2 * i + (lane >> 5); scr[kk * 33 + (lane & 31)] = W[(size_t)(k0 + kk) * N + c0 + n0 + (lane & 31)] * scale; }
;     asm volatile("s_waitcnt lgkmcnt(0)" ::: "memory");
.LBB0_237:
	s_lshl_b32 s35, s0, 1
	s_lshl_b32 s36, s5, 1
	v_or_b32_e32 v36, s36, v2
	s_add_i32 s37, s35, 4
	s_add_i32 s38, s36, 4
	s_add_i32 s39, s35, 8
	s_add_i32 s40, s36, 8
	s_add_i32 s41, s35, 12
	s_add_i32 s44, s36, 12
	s_add_i32 s45, s35, 16
	s_add_i32 s46, s36, 16
	s_add_i32 s47, s35, 20
	s_add_i32 s48, s36, 20
	s_add_i32 s49, s35, 24
	s_add_i32 s50, s36, 24
	s_add_i32 s51, s35, 28
	s_add_i32 s52, s36, 28
	v_or_b32_e32 v34, s35, v5
	v_ashrrev_i32_e32 v37, 31, v36
	v_or_b32_e32 v38, s37, v5
	v_or_b32_e32 v40, s38, v2
	v_or_b32_e32 v42, s39, v5
	v_or_b32_e32 v44, s40, v2
	v_or_b32_e32 v46, s41, v5
	v_or_b32_e32 v48, s44, v2
	v_or_b32_e32 v50, s45, v5
	v_or_b32_e32 v52, s46, v2
	v_or_b32_e32 v54, s47, v5
	v_or_b32_e32 v56, s48, v2
	v_or_b32_e32 v58, s49, v5
	v_or_b32_e32 v60, s50, v2
	v_or_b32_e32 v62, s51, v5
	v_or_b32_e32 v64, s52, v2
	v_ashrrev_i32_e32 v35, 31, v34
	v_lshlrev_b64 v[36:37], 12, v[36:37]
	v_ashrrev_i32_e32 v41, 31, v40
	v_ashrrev_i32_e32 v39, 31, v38
	v_ashrrev_i32_e32 v45, 31, v44
	v_ashrrev_i32_e32 v43, 31, v42
	v_ashrrev_i32_e32 v49, 31, v48
	v_ashrrev_i32_e32 v47, 31, v46
	v_ashrrev_i32_e32 v53, 31, v52
	v_ashrrev_i32_e32 v51, 31, v50
	v_ashrrev_i32_e32 v57, 31, v56
	v_ashrrev_i32_e32 v55, 31, v54
	v_ashrrev_i32_e32 v61, 31, v60
	v_ashrrev_i32_e32 v59, 31, v58
	v_ashrrev_i32_e32 v65, 31, v64
	v_ashrrev_i32_e32 v63, 31, v62
	v_lshlrev_b64 v[34:35], 12, v[34:35]
	v_lshl_add_u64 v[36:37], v[26:27], 0, v[36:37]
	v_lshlrev_b64 v[38:39], 12, v[38:39]
	v_lshlrev_b64 v[40:41], 12, v[40:41]
	v_lshlrev_b64 v[42:43], 12, v[42:43]
	v_lshlrev_b64 v[44:45], 12, v[44:45]
	v_lshlrev_b64 v[46:47], 12, v[46:47]
	v_lshlrev_b64 v[48:49], 12, v[48:49]
	v_lshlrev_b64 v[50:51], 12, v[50:51]
	v_lshlrev_b64 v[52:53], 12, v[52:53]
	v_lshlrev_b64 v[54:55], 12, v[54:55]
	v_lshlrev_b64 v[56:57], 12, v[56:57]
	v_lshlrev_b64 v[58:59], 12, v[58:59]
	v_lshlrev_b64 v[60:61], 12, v[60:61]
	v_lshlrev_b64 v[62:63], 12, v[62:63]
	v_lshlrev_b64 v[64:65], 12, v[64:65]
	v_lshl_add_u64 v[34:35], v[26:27], 0, v[34:35]
	v_lshl_add_u64 v[40:41], v[26:27], 0, v[40:41]
	v_lshl_add_u64 v[38:39], v[26:27], 0, v[38:39]
	v_lshl_add_u64 v[44:45], v[26:27], 0, v[44:45]
	v_lshl_add_u64 v[42:43], v[26:27], 0, v[42:43]
	v_lshl_add_u64 v[48:49], v[26:27], 0, v[48:49]
	v_lshl_add_u64 v[46:47], v[26:27], 0, v[46:47]
	v_lshl_add_u64 v[52:53], v[26:27], 0, v[52:53]
	v_lshl_add_u64 v[50:51], v[26:27], 0, v[50:51]
	v_lshl_add_u64 v[56:57], v[26:27], 0, v[56:57]
	v_lshl_add_u64 v[54:55], v[26:27], 0, v[54:55]
	v_lshl_add_u64 v[60:61], v[26:27], 0, v[60:61]
	v_lshl_add_u64 v[58:59], v[26:27], 0, v[58:59]
	v_lshl_add_u64 v[64:65], v[26:27], 0, v[64:65]
	v_lshl_add_u64 v[62:63], v[26:27], 0, v[62:63]
	global_load_dword v25, v[36:37], off nt
	global_load_dword v28, v[34:35], off nt
	global_load_dword v66, v[40:41], off nt
	global_load_dword v67, v[38:39], off nt
	global_load_dword v68, v[44:45], off nt
	global_load_dword v69, v[42:43], off nt
	global_load_dword v70, v[48:49], off nt
	global_load_dword v71, v[46:47], off nt
	global_load_dword v72, v[52:53], off nt
	global_load_dword v73, v[50:51], off nt
	global_load_dword v74, v[56:57], off nt
	global_load_dword v75, v[54:55], off nt
	global_load_dword v76, v[60:61], off nt
	global_load_dword v77, v[58:59], off nt
	global_load_dword v78, v[64:65], off nt
	global_load_dword v79, v[62:63], off nt
	v_or_b32_e32 v36, s35, v1
	v_or_b32_e32 v34, s36, v0
	s_add_i32 s5, s5, 16
	s_add_i32 s0, s0, 16
	s_add_i32 s29, s29, -16
	v_mad_u64_u32 v[34:35], s[42:43], v34, s31, v[4:5]
	v_mad_u64_u32 v[36:37], s[42:43], v36, s31, v[4:5]
	v_or_b32_e32 v35, s37, v1
	v_or_b32_e32 v37, s38, v0
	v_or_b32_e32 v44, s39, v1
	v_or_b32_e32 v42, s40, v0
	v_or_b32_e32 v48, s41, v1
	v_or_b32_e32 v46, s44, v0
	v_or_b32_e32 v52, s45, v1
	v_or_b32_e32 v50, s46, v0
	v_or_b32_e32 v56, s47, v1
	v_or_b32_e32 v54, s48, v0
	v_or_b32_e32 v60, s49, v1
	v_or_b32_e32 v58, s50, v0
	v_or_b32_e32 v64, s51, v1
	v_or_b32_e32 v62, s52, v0
	s_cmp_lg_u32 s29, 0
	v_mad_u64_u32 v[38:39], s[36:37], v37, s31, v[4:5]
	v_mad_u64_u32 v[40:41], s[36:37], v35, s31, v[4:5]
	v_mad_u64_u32 v[42:43], s[36:37], v42, s31, v[4:5]
	v_mad_u64_u32 v[44:45], s[36:37], v44, s31, v[4:5]
	v_mad_u64_u32 v[46:47], s[36:37], v46, s31, v[4:5]
	v_mad_u64_u32 v[48:49], s[36:37], v48, s31, v[4:5]
	v_mad_u64_u32 v[50:51], s[36:37], v50, s31, v[4:5]
	v_mad_u64_u32 v[52:53], s[36:37], v52, s31, v[4:5]
	v_mad_u64_u32 v[54:55], s[36:37], v54, s31, v[4:5]
	v_mad_u64_u32 v[56:57], s[36:37], v56, s31, v[4:5]
	v_mad_u64_u32 v[58:59], s[36:37], v58, s31, v[4:5]
	v_mad_u64_u32 v[60:61], s[36:37], v60, s31, v[4:5]
	v_mad_u64_u32 v[62:63], s[36:37], v62, s31, v[4:5]
	v_mad_u64_u32 v[64:65], s[36:37], v64, s31, v[4:5]
	s_waitcnt vmcnt(0)
	ds_write_b32 v34, v25
	ds_write_b32 v36, v28
	ds_write_b32 v38, v66
	ds_write_b32 v40, v67
	ds_write_b32 v42, v68
	ds_write_b32 v44, v69
	ds_write_b32 v46, v70
	ds_write_b32 v48, v71
	ds_write_b32 v50, v72
	ds_write_b32 v52, v73
	ds_write_b32 v54, v74
	ds_write_b32 v56, v75
	ds_write_b32 v58, v76
	ds_write_b32 v60, v77
	ds_write_b32 v62, v78
	ds_write_b32 v64, v79
	s_cbranch_scc1 .LBB0_237
; #define LAS __attribute__((address_space(3)))
; __device__ __forceinline__ unsigned cvtpk(float lo, float hi) { return pg8::cvt_pk_bf16(lo, hi); }
; __device__ __forceinline__ void transpose_item(const float* W, int K, int N, int c0, int ncols, bf16_t* WT, int row_off, float scale, LAS float* scr, int item, int lane) {
;     ...
;     const int c = lane & 7;
; #pragma unroll
;     for (int j = 0; j < 4; ++j) { const int n = (lane >> 3) + 8 * j; const LAS float* s = scr + (8 * c) * 33 + n;
;         u32x4 o; o.x = cvtpk(s[0 * 33], s[1 * 33]); o.y = cvtpk(s[2 * 33], s[3 * 33]); o.z = cvtpk(s[4 * 33], s[5 * 33]); o.w = cvtpk(s[6 * 33], s[7 * 33]);
;         *(u32x4*)(WT + (size_t)(row_off + n0 + n) * K + k0 + 8 * c) = o; }
;     asm volatile("s_waitcnt lgkmcnt(0)" ::: "memory");
	s_waitcnt lgkmcnt(0)
	ds_read2_b32 v[26:27], v30 offset0:33 offset1:41
	ds_read2_b32 v[38:39], v30 offset1:8
	ds_read2_b32 v[40:41], v30 offset0:66 offset1:74
	ds_read2_b32 v[42:43], v30 offset0:99 offset1:107
	ds_read2_b32 v[44:45], v30 offset0:132 offset1:140
	ds_read2_b32 v[46:47], v30 offset0:165 offset1:173
	ds_read2_b32 v[48:49], v30 offset0:198 offset1:206
	ds_read2_b32 v[50:51], v30 offset0:231 offset1:239
	v_or_b32_e32 v54, s4, v29
	s_ashr_i32 s29, s28, 31
	v_ashrrev_i32_e32 v55, 31, v54
	v_lshl_add_u64 v[52:53], s[28:29], 1, v[16:17]
	v_lshlrev_b64 v[54:55], 10, v[54:55]
	s_waitcnt lgkmcnt(6)
	v_cvt_pk_bf16_f32 v34, v38, v26
	s_waitcnt lgkmcnt(4)
	v_cvt_pk_bf16_f32 v35, v40, v42
	s_waitcnt lgkmcnt(2)
	v_cvt_pk_bf16_f32 v36, v44, v46
	s_waitcnt lgkmcnt(0)
	v_cvt_pk_bf16_f32 v37, v48, v50
	v_lshl_add_u64 v[54:55], v[52:53], 0, v[54:55]
	v_or_b32_e32 v26, s4, v31
	global_store_dwordx4 v[54:55], v[34:37], off
	s_nop 1
	v_cvt_pk_bf16_f32 v34, v39, v27
	v_ashrrev_i32_e32 v27, 31, v26
	v_cvt_pk_bf16_f32 v35, v41, v43
	v_cvt_pk_bf16_f32 v36, v45, v47
	v_cvt_pk_bf16_f32 v37, v49, v51
	v_lshlrev_b64 v[26:27], 10, v[26:27]
	ds_read2_b32 v[38:39], v30 offset0:49 offset1:57
	ds_read2_b32 v[40:41], v30 offset0:16 offset1:24
	ds_read2_b32 v[42:43], v30 offset0:82 offset1:90
	ds_read2_b32 v[44:45], v30 offset0:115 offset1:123
	ds_read2_b32 v[46:47], v30 offset0:148 offset1:156
	ds_read2_b32 v[48:49], v30 offset0:181 offset1:189
	ds_read2_b32 v[50:51], v30 offset0:214 offset1:222
	ds_read2_b32 v[54:55], v30 offset0:247 offset1:255
	v_lshl_add_u64 v[26:27], v[52:53], 0, v[26:27]
	global_store_dwordx4 v[26:27], v[34:37], off
	v_or_b32_e32 v26, s4, v32
	v_ashrrev_i32_e32 v27, 31, v26
	v_lshlrev_b64 v[26:27], 10, v[26:27]
	s_waitcnt lgkmcnt(6)
	v_cvt_pk_bf16_f32 v34, v40, v38
	s_waitcnt lgkmcnt(4)
	v_cvt_pk_bf16_f32 v35, v42, v44
	s_waitcnt lgkmcnt(2)
	v_cvt_pk_bf16_f32 v36, v46, v48
	s_waitcnt lgkmcnt(0)
	v_cvt_pk_bf16_f32 v37, v50, v54
	v_lshl_add_u64 v[26:27], v[52:53], 0, v[26:27]
	global_store_dwordx4 v[26:27], v[34:37], off
	v_or_b32_e32 v26, s4, v33
	v_ashrrev_i32_e32 v27, 31, v26
	v_lshlrev_b64 v[26:27], 10, v[26:27]
	v_cvt_pk_bf16_f32 v34, v41, v39
	v_cvt_pk_bf16_f32 v35, v43, v45
	v_cvt_pk_bf16_f32 v36, v47, v49
	v_cvt_pk_bf16_f32 v37, v51, v55
	v_lshl_add_u64 v[26:27], v[52:53], 0, v[26:27]
	global_store_dwordx4 v[26:27], v[34:37], off
	s_waitcnt lgkmcnt(0)

; __device__ __forceinline__ void transpose_item(const float* W, int K, int N, int c0, int ncols, bf16_t* WT, int row_off, float scale, LAS float* scr, int item, int lane) {
;     ...
; #pragma unroll 8
;     for (int i = 0; i < 32; ++i) { const int kk = 2 * i + (lane >> 5); scr[kk * 33 + (lane & 31)] = W[(size_t)(k0 + kk) * N + c0 + n0 + (lane & 31)] * scale; }
;     asm volatile("s_waitcnt lgkmcnt(0)" ::: "memory");
.LBB0_244:
	s_lshl_b32 s35, s0, 1
	s_lshl_b32 s36, s5, 1
	v_or_b32_e32 v36, s36, v2
	s_add_i32 s37, s35, 4
	s_add_i32 s38, s36, 4
	s_add_i32 s39, s35, 8
	s_add_i32 s40, s36, 8
	s_add_i32 s41, s35, 12
	s_add_i32 s44, s36, 12
	s_add_i32 s45, s35, 16
	s_add_i32 s46, s36, 16
	s_add_i32 s47, s35, 20
	s_add_i32 s48, s36, 20
	s_add_i32 s49, s35, 24
	s_add_i32 s50, s36, 24
	s_add_i32 s51, s35, 28
	s_add_i32 s52, s36, 28
	v_or_b32_e32 v34, s35, v5
	v_ashrrev_i32_e32 v37, 31, v36
	v_or_b32_e32 v38, s37, v5
	v_or_b32_e32 v40, s38, v2
	v_or_b32_e32 v42, s39, v5
	v_or_b32_e32 v44, s40, v2
	v_or_b32_e32 v46, s41, v5
	v_or_b32_e32 v48, s44, v2
	v_or_b32_e32 v50, s45, v5
	v_or_b32_e32 v52, s46, v2
	v_or_b32_e32 v54, s47, v5
	v_or_b32_e32 v56, s48, v2
	v_or_b32_e32 v58, s49, v5
	v_or_b32_e32 v60, s50, v2
	v_or_b32_e32 v62, s51, v5
	v_or_b32_e32 v64, s52, v2
	v_ashrrev_i32_e32 v35, 31, v34
	v_lshlrev_b64 v[36:37], 12, v[36:37]
	v_ashrrev_i32_e32 v41, 31, v40
	v_ashrrev_i32_e32 v39, 31, v38
	v_ashrrev_i32_e32 v45, 31, v44
	v_ashrrev_i32_e32 v43, 31, v42
	v_ashrrev_i32_e32 v49, 31, v48
	v_ashrrev_i32_e32 v47, 31, v46
	v_ashrrev_i32_e32 v53, 31, v52
	v_ashrrev_i32_e32 v51, 31, v50
	v_ashrrev_i32_e32 v57, 31, v56
	v_ashrrev_i32_e32 v55, 31, v54
	v_ashrrev_i32_e32 v61, 31, v60
	v_ashrrev_i32_e32 v59, 31, v58
	v_ashrrev_i32_e32 v65, 31, v64
	v_ashrrev_i32_e32 v63, 31, v62
	v_lshlrev_b64 v[34:35], 12, v[34:35]
	v_lshl_add_u64 v[36:37], v[26:27], 0, v[36:37]
	v_lshlrev_b64 v[38:39], 12, v[38:39]
	v_lshlrev_b64 v[40:41], 12, v[40:41]
	v_lshlrev_b64 v[42:43], 12, v[42:43]
	v_lshlrev_b64 v[44:45], 12, v[44:45]
	v_lshlrev_b64 v[46:47], 12, v[46:47]
	v_lshlrev_b64 v[48:49], 12, v[48:49]
	v_lshlrev_b64 v[50:51], 12, v[50:51]
	v_lshlrev_b64 v[52:53], 12, v[52:53]
	v_lshlrev_b64 v[54:55], 12, v[54:55]
	v_lshlrev_b64 v[56:57], 12, v[56:57]
	v_lshlrev_b64 v[58:59], 12, v[58:59]
	v_lshlrev_b64 v[60:61], 12, v[60:61]
	v_lshlrev_b64 v[62:63], 12, v[62:63]
	v_lshlrev_b64 v[64:65], 12, v[64:65]
	v_lshl_add_u64 v[34:35], v[26:27], 0, v[34:35]
	v_lshl_add_u64 v[40:41], v[26:27], 0, v[40:41]
	v_lshl_add_u64 v[38:39], v[26:27], 0, v[38:39]
	v_lshl_add_u64 v[44:45], v[26:27], 0, v[44:45]
	v_lshl_add_u64 v[42:43], v[26:27], 0, v[42:43]
	v_lshl_add_u64 v[48:49], v[26:27], 0, v[48:49]
	v_lshl_add_u64 v[46:47], v[26:27], 0, v[46:47]
	v_lshl_add_u64 v[52:53], v[26:27], 0, v[52:53]
	v_lshl_add_u64 v[50:51], v[26:27], 0, v[50:51]
	v_lshl_add_u64 v[56:57], v[26:27], 0, v[56:57]
	v_lshl_add_u64 v[54:55], v[26:27], 0, v[54:55]
	v_lshl_add_u64 v[60:61], v[26:27], 0, v[60:61]
	v_lshl_add_u64 v[58:59], v[26:27], 0, v[58:59]
	v_lshl_add_u64 v[64:65], v[26:27], 0, v[64:65]
	v_lshl_add_u64 v[62:63], v[26:27], 0, v[62:63]
	global_load_dword v25, v[36:37], off nt
	global_load_dword v28, v[34:35], off nt
	global_load_dword v66, v[40:41], off nt
	global_load_dword v67, v[38:39], off nt
	global_load_dword v68, v[44:45], off nt
	global_load_dword v69, v[42:43], off nt
	global_load_dword v70, v[48:49], off nt
	global_load_dword v71, v[46:47], off nt
	global_load_dword v72, v[52:53], off nt
	global_load_dword v73, v[50:51], off nt
	global_load_dword v74, v[56:57], off nt
	global_load_dword v75, v[54:55], off nt
	global_load_dword v76, v[60:61], off nt
	global_load_dword v77, v[58:59], off nt
	global_load_dword v78, v[64:65], off nt
	global_load_dword v79, v[62:63], off nt
	v_or_b32_e32 v36, s35, v1
	v_or_b32_e32 v34, s36, v0
	s_add_i32 s5, s5, 16
	s_add_i32 s0, s0, 16
	s_add_i32 s29, s29, -16
	v_mad_u64_u32 v[34:35], s[42:43], v34, s31, v[4:5]
	v_mad_u64_u32 v[36:37], s[42:43], v36, s31, v[4:5]
	v_or_b32_e32 v35, s37, v1
	v_or_b32_e32 v37, s38, v0
	v_or_b32_e32 v44, s39, v1
	v_or_b32_e32 v42, s40, v0
	v_or_b32_e32 v48, s41, v1
	v_or_b32_e32 v46, s44, v0
	v_or_b32_e32 v52, s45, v1
	v_or_b32_e32 v50, s46, v0
	v_or_b32_e32 v56, s47, v1
	v_or_b32_e32 v54, s48, v0
	v_or_b32_e32 v60, s49, v1
	v_or_b32_e32 v58, s50, v0
	v_or_b32_e32 v64, s51, v1
	v_or_b32_e32 v62, s52, v0
	s_cmp_lg_u32 s29, 0
	v_mad_u64_u32 v[38:39], s[36:37], v37, s31, v[4:5]
	v_mad_u64_u32 v[40:41], s[36:37], v35, s31, v[4:5]
	v_mad_u64_u32 v[42:43], s[36:37], v42, s31, v[4:5]
	v_mad_u64_u32 v[44:45], s[36:37], v44, s31, v[4:5]
	v_mad_u64_u32 v[46:47], s[36:37], v46, s31, v[4:5]
	v_mad_u64_u32 v[48:49], s[36:37], v48, s31, v[4:5]
	v_mad_u64_u32 v[50:51], s[36:37], v50, s31, v[4:5]
	v_mad_u64_u32 v[52:53], s[36:37], v52, s31, v[4:5]
	v_mad_u64_u32 v[54:55], s[36:37], v54, s31, v[4:5]
	v_mad_u64_u32 v[56:57], s[36:37], v56, s31, v[4:5]
	v_mad_u64_u32 v[58:59], s[36:37], v58, s31, v[4:5]
	v_mad_u64_u32 v[60:61], s[36:37], v60, s31, v[4:5]
	v_mad_u64_u32 v[62:63], s[36:37], v62, s31, v[4:5]
	v_mad_u64_u32 v[64:65], s[36:37], v64, s31, v[4:5]
	s_waitcnt vmcnt(0)
	ds_write_b32 v34, v25
	ds_write_b32 v36, v28
	ds_write_b32 v38, v66
	ds_write_b32 v40, v67
	ds_write_b32 v42, v68
	ds_write_b32 v44, v69
	ds_write_b32 v46, v70
	ds_write_b32 v48, v71
	ds_write_b32 v50, v72
	ds_write_b32 v52, v73
	ds_write_b32 v54, v74
	ds_write_b32 v56, v75
	ds_write_b32 v58, v76
	ds_write_b32 v60, v77
	ds_write_b32 v62, v78
	ds_write_b32 v64, v79
	s_cbranch_scc1 .LBB0_244
; #define LAS __attribute__((address_space(3)))
; __device__ __forceinline__ unsigned cvtpk(float lo, float hi) { return pg8::cvt_pk_bf16(lo, hi); }
; __device__ __forceinline__ void transpose_item(const float* W, int K, int N, int c0, int ncols, bf16_t* WT, int row_off, float scale, LAS float* scr, int item, int lane) {
;     ...
;     const int c = lane & 7;
; #pragma unroll
;     for (int j = 0; j < 4; ++j) { const int n = (lane >> 3) + 8 * j; const LAS float* s = scr + (8 * c) * 33 + n;
;         u32x4 o; o.x = cvtpk(s[0 * 33], s[1 * 33]); o.y = cvtpk(s[2 * 33], s[3 * 33]); o.z = cvtpk(s[4 * 33], s[5 * 33]); o.w = cvtpk(s[6 * 33], s[7 * 33]);
;         *(u32x4*)(WT + (size_t)(row_off + n0 + n) * K + k0 + 8 * c) = o; }
;     asm volatile("s_waitcnt lgkmcnt(0)" ::: "memory");
	s_waitcnt lgkmcnt(0)
	ds_read2_b32 v[26:27], v30 offset0:33 offset1:41
	ds_read2_b32 v[38:39], v30 offset1:8
	ds_read2_b32 v[40:41], v30 offset0:66 offset1:74
	ds_read2_b32 v[42:43], v30 offset0:99 offset1:107
	ds_read2_b32 v[44:45], v30 offset0:132 offset1:140
	ds_read2_b32 v[46:47], v30 offset0:165 offset1:173
	ds_read2_b32 v[48:49], v30 offset0:198 offset1:206
	ds_read2_b32 v[50:51], v30 offset0:231 offset1:239
	v_or_b32_e32 v54, s4, v29
	s_ashr_i32 s29, s28, 31
	v_ashrrev_i32_e32 v55, 31, v54
	v_lshl_add_u64 v[52:53], s[28:29], 1, v[18:19]
	v_lshlrev_b64 v[54:55], 11, v[54:55]
	s_waitcnt lgkmcnt(6)
	v_cvt_pk_bf16_f32 v34, v38, v26
	s_waitcnt lgkmcnt(4)
	v_cvt_pk_bf16_f32 v35, v40, v42
	s_waitcnt lgkmcnt(2)
	v_cvt_pk_bf16_f32 v36, v44, v46
	s_waitcnt lgkmcnt(0)
	v_cvt_pk_bf16_f32 v37, v48, v50
	v_lshl_add_u64 v[54:55], v[52:53], 0, v[54:55]
	v_or_b32_e32 v26, s4, v31
	global_store_dwordx4 v[54:55], v[34:37], off
	s_nop 1
	v_cvt_pk_bf16_f32 v34, v39, v27
	v_ashrrev_i32_e32 v27, 31, v26
	v_cvt_pk_bf16_f32 v35, v41, v43
	v_cvt_pk_bf16_f32 v36, v45, v47
	v_cvt_pk_bf16_f32 v37, v49, v51
	v_lshlrev_b64 v[26:27], 11, v[26:27]
	ds_read2_b32 v[38:39], v30 offset0:49 offset1:57
	ds_read2_b32 v[40:41], v30 offset0:16 offset1:24
	ds_read2_b32 v[42:43], v30 offset0:82 offset1:90
	ds_read2_b32 v[44:45], v30 offset0:115 offset1:123
	ds_read2_b32 v[46:47], v30 offset0:148 offset1:156
	ds_read2_b32 v[48:49], v30 offset0:181 offset1:189
	ds_read2_b32 v[50:51], v30 offset0:214 offset1:222
	ds_read2_b32 v[54:55], v30 offset0:247 offset1:255
	v_lshl_add_u64 v[26:27], v[52:53], 0, v[26:27]
	global_store_dwordx4 v[26:27], v[34:37], off
	v_or_b32_e32 v26, s4, v32
	v_ashrrev_i32_e32 v27, 31, v26
	v_lshlrev_b64 v[26:27], 11, v[26:27]
	s_waitcnt lgkmcnt(6)
	v_cvt_pk_bf16_f32 v34, v40, v38
	s_waitcnt lgkmcnt(4)
	v_cvt_pk_bf16_f32 v35, v42, v44
	s_waitcnt lgkmcnt(2)
	v_cvt_pk_bf16_f32 v36, v46, v48
	s_waitcnt lgkmcnt(0)
	v_cvt_pk_bf16_f32 v37, v50, v54
	v_lshl_add_u64 v[26:27], v[52:53], 0, v[26:27]
	global_store_dwordx4 v[26:27], v[34:37], off
	v_or_b32_e32 v26, s4, v33
	v_ashrrev_i32_e32 v27, 31, v26
	v_lshlrev_b64 v[26:27], 11, v[26:27]
	v_cvt_pk_bf16_f32 v34, v41, v39
	v_cvt_pk_bf16_f32 v35, v43, v45
	v_cvt_pk_bf16_f32 v36, v47, v49
	v_cvt_pk_bf16_f32 v37, v51, v55
	v_lshl_add_u64 v[26:27], v[52:53], 0, v[26:27]
	global_store_dwordx4 v[26:27], v[34:37], off
	s_waitcnt lgkmcnt(0)

; __device__ __forceinline__ void transpose_item(const float* W, int K, int N, int c0, int ncols, bf16_t* WT, int row_off, float scale, LAS float* scr, int item, int lane) {
;     ...
; #pragma unroll 8
;     for (int i = 0; i < 32; ++i) { const int kk = 2 * i + (lane >> 5); scr[kk * 33 + (lane & 31)] = W[(size_t)(k0 + kk) * N + c0 + n0 + (lane & 31)] * scale; }
;     asm volatile("s_waitcnt lgkmcnt(0)" ::: "memory");
.LBB0_251:
	s_lshl_b32 s28, s3, 1
	s_lshl_b32 s29, s0, 1
	v_or_b32_e32 v2, s29, v28
	s_add_i32 s35, s28, 4
	s_add_i32 s36, s29, 4
	v_mov_b32_e32 v37, v3
	s_add_i32 s38, s29, 8
	v_lshlrev_b64 v[50:51], 12, v[2:3]
	v_or_b32_e32 v36, s35, v5
	v_or_b32_e32 v2, s36, v28
	v_mov_b32_e32 v35, v3
	v_or_b32_e32 v34, s28, v5
	s_add_i32 s40, s29, 12
	v_lshlrev_b64 v[36:37], 12, v[36:37]
	v_lshlrev_b64 v[52:53], 12, v[2:3]
	v_or_b32_e32 v2, s38, v28
	s_add_i32 s37, s28, 8
	s_add_i32 s39, s28, 12
	s_add_i32 s42, s29, 16
	v_lshlrev_b64 v[34:35], 12, v[34:35]
	v_lshl_add_u64 v[50:51], v[26:27], 0, v[50:51]
	v_lshl_add_u64 v[36:37], v[26:27], 0, v[36:37]
	v_lshlrev_b64 v[54:55], 12, v[2:3]
	v_or_b32_e32 v2, s40, v28
	v_mov_b32_e32 v39, v3
	v_mov_b32_e32 v41, v3
	s_add_i32 s44, s29, 20
	v_or_b32_e32 v38, s37, v5
	v_or_b32_e32 v40, s39, v5
	v_lshl_add_u64 v[34:35], v[26:27], 0, v[34:35]
	v_lshl_add_u64 v[52:53], v[26:27], 0, v[52:53]
	global_load_dword v25, v[50:51], off nt
	global_load_dword v66, v[34:35], off nt
	global_load_dword v67, v[52:53], off nt
	global_load_dword v68, v[36:37], off nt
	v_lshlrev_b64 v[36:37], 12, v[2:3]
	v_or_b32_e32 v2, s42, v28
	s_add_i32 s41, s28, 16
	s_add_i32 s43, s28, 20
	s_add_i32 s46, s29, 24
	v_lshlrev_b64 v[38:39], 12, v[38:39]
	v_lshlrev_b64 v[40:41], 12, v[40:41]
	v_lshl_add_u64 v[34:35], v[26:27], 0, v[54:55]
	v_lshl_add_u64 v[36:37], v[26:27], 0, v[36:37]
	v_lshlrev_b64 v[50:51], 12, v[2:3]
	v_or_b32_e32 v2, s44, v28
	v_mov_b32_e32 v43, v3
	v_mov_b32_e32 v45, v3
	s_add_i32 s45, s28, 24
	s_add_i32 s47, s28, 28
	s_add_i32 s48, s29, 28
	v_or_b32_e32 v42, s41, v5
	v_or_b32_e32 v44, s43, v5
	v_lshl_add_u64 v[38:39], v[26:27], 0, v[38:39]
	v_lshl_add_u64 v[40:41], v[26:27], 0, v[40:41]
	global_load_dword v69, v[34:35], off nt
	global_load_dword v70, v[38:39], off nt
	global_load_dword v71, v[36:37], off nt
	global_load_dword v72, v[40:41], off nt
	v_lshlrev_b64 v[36:37], 12, v[2:3]
	v_or_b32_e32 v2, s46, v28
	v_mov_b32_e32 v47, v3
	v_mov_b32_e32 v49, v3
	v_or_b32_e32 v46, s45, v5
	v_or_b32_e32 v48, s47, v5
	v_lshlrev_b64 v[42:43], 12, v[42:43]
	v_lshlrev_b64 v[44:45], 12, v[44:45]
	v_lshl_add_u64 v[34:35], v[26:27], 0, v[50:51]
	v_lshl_add_u64 v[36:37], v[26:27], 0, v[36:37]
	v_lshlrev_b64 v[38:39], 12, v[2:3]
	v_or_b32_e32 v2, s48, v28
	v_lshlrev_b64 v[46:47], 12, v[46:47]
	v_lshlrev_b64 v[48:49], 12, v[48:49]
	v_lshl_add_u64 v[42:43], v[26:27], 0, v[42:43]
	v_lshl_add_u64 v[44:45], v[26:27], 0, v[44:45]
	global_load_dword v73, v[34:35], off nt
	global_load_dword v74, v[42:43], off nt
	global_load_dword v75, v[36:37], off nt
	global_load_dword v76, v[44:45], off nt
	v_lshl_add_u64 v[34:35], v[26:27], 0, v[38:39]
	v_lshlrev_b64 v[36:37], 12, v[2:3]
	v_lshl_add_u64 v[46:47], v[26:27], 0, v[46:47]
	v_lshl_add_u64 v[48:49], v[26:27], 0, v[48:49]
	v_lshl_add_u64 v[36:37], v[26:27], 0, v[36:37]
	global_load_dword v2, v[34:35], off nt
	global_load_dword v77, v[46:47], off nt
	global_load_dword v78, v[36:37], off nt
	global_load_dword v79, v[48:49], off nt
	v_or_b32_e32 v36, s28, v1
	v_or_b32_e32 v34, s29, v0
	s_add_i32 s0, s0, 16
	s_add_i32 s3, s3, 16
	s_add_i32 s5, s5, -16
	v_mad_u64_u32 v[34:35], s[28:29], v34, s31, v[4:5]
	v_mad_u64_u32 v[36:37], s[28:29], v36, s31, v[4:5]
	v_or_b32_e32 v35, s35, v1
	v_or_b32_e32 v37, s36, v0
	v_or_b32_e32 v44, s37, v1
	v_or_b32_e32 v42, s38, v0
	v_or_b32_e32 v48, s39, v1
	v_or_b32_e32 v46, s40, v0
	v_or_b32_e32 v52, s41, v1
	v_or_b32_e32 v50, s42, v0
	v_or_b32_e32 v56, s43, v1
	v_or_b32_e32 v54, s44, v0
	v_or_b32_e32 v60, s45, v1
	v_or_b32_e32 v58, s46, v0
	v_or_b32_e32 v64, s47, v1
	v_or_b32_e32 v62, s48, v0
	s_cmp_lg_u32 s5, 0
	v_mad_u64_u32 v[38:39], s[28:29], v37, s31, v[4:5]
	v_mad_u64_u32 v[40:41], s[28:29], v35, s31, v[4:5]
	v_mad_u64_u32 v[42:43], s[28:29], v42, s31, v[4:5]
	v_mad_u64_u32 v[44:45], s[28:29], v44, s31, v[4:5]
	v_mad_u64_u32 v[46:47], s[28:29], v46, s31, v[4:5]
	v_mad_u64_u32 v[48:49], s[28:29], v48, s31, v[4:5]
	v_mad_u64_u32 v[50:51], s[28:29], v50, s31, v[4:5]
	v_mad_u64_u32 v[52:53], s[28:29], v52, s31, v[4:5]
	v_mad_u64_u32 v[54:55], s[28:29], v54, s31, v[4:5]
	v_mad_u64_u32 v[56:57], s[28:29], v56, s31, v[4:5]
	v_mad_u64_u32 v[58:59], s[28:29], v58, s31, v[4:5]
	v_mad_u64_u32 v[60:61], s[28:29], v60, s31, v[4:5]
	v_mad_u64_u32 v[62:63], s[28:29], v62, s31, v[4:5]
	v_mad_u64_u32 v[64:65], s[28:29], v64, s31, v[4:5]
	s_waitcnt vmcnt(0)
	ds_write_b32 v34, v25
	ds_write_b32 v36, v66
	ds_write_b32 v38, v67
	ds_write_b32 v40, v68
	ds_write_b32 v42, v69
	ds_write_b32 v44, v70
	ds_write_b32 v46, v71
	ds_write_b32 v48, v72
	ds_write_b32 v50, v73
	ds_write_b32 v52, v74
	ds_write_b32 v54, v75
	ds_write_b32 v56, v76
	ds_write_b32 v58, v2
	ds_write_b32 v60, v77
	ds_write_b32 v62, v78
	ds_write_b32 v64, v79
	s_cbranch_scc1 .LBB0_251
; #define LAS __attribute__((address_space(3)))
; __device__ __forceinline__ unsigned cvtpk(float lo, float hi) { return pg8::cvt_pk_bf16(lo, hi); }
; __device__ __forceinline__ void transpose_item(const float* W, int K, int N, int c0, int ncols, bf16_t* WT, int row_off, float scale, LAS float* scr, int item, int lane) {
;     ...
;     const int c = lane & 7;
; #pragma unroll
;     for (int j = 0; j < 4; ++j) { const int n = (lane >> 3) + 8 * j; const LAS float* s = scr + (8 * c) * 33 + n;
;         u32x4 o; o.x = cvtpk(s[0 * 33], s[1 * 33]); o.y = cvtpk(s[2 * 33], s[3 * 33]); o.z = cvtpk(s[4 * 33], s[5 * 33]); o.w = cvtpk(s[6 * 33], s[7 * 33]);
;         *(u32x4*)(WT + (size_t)(row_off + n0 + n) * K + k0 + 8 * c) = o; }
;     asm volatile("s_waitcnt lgkmcnt(0)" ::: "memory");
	s_waitcnt lgkmcnt(0)
	ds_read2_b32 v[26:27], v30 offset0:33 offset1:41
	ds_read2_b32 v[38:39], v30 offset1:8
	ds_read2_b32 v[40:41], v30 offset0:66 offset1:74
	ds_read2_b32 v[42:43], v30 offset0:99 offset1:107
	ds_read2_b32 v[44:45], v30 offset0:132 offset1:140
	ds_read2_b32 v[46:47], v30 offset0:165 offset1:173
	ds_read2_b32 v[48:49], v30 offset0:198 offset1:206
	ds_read2_b32 v[50:51], v30 offset0:231 offset1:239
	v_or_b32_e32 v2, s2, v29
	s_lshl_b32 s0, s4, 1
	v_mul_u32_u24_e32 v2, 0xb00, v2
	v_lshl_add_u64 v[52:53], v[20:21], 0, s[0:1]
	v_lshlrev_b32_e32 v2, 1, v2
	v_lshl_add_u64 v[54:55], v[52:53], 0, v[2:3]
	v_or_b32_e32 v2, s2, v31
	s_waitcnt lgkmcnt(6)
	v_cvt_pk_bf16_f32 v34, v38, v26
	s_waitcnt lgkmcnt(4)
	v_cvt_pk_bf16_f32 v35, v40, v42
	s_waitcnt lgkmcnt(2)
	v_cvt_pk_bf16_f32 v36, v44, v46
	s_waitcnt lgkmcnt(0)
	v_cvt_pk_bf16_f32 v37, v48, v50
	v_mul_u32_u24_e32 v2, 0xb00, v2
	global_store_dwordx4 v[54:55], v[34:37], off
	v_lshlrev_b32_e32 v2, 1, v2
	s_nop 0
	v_cvt_pk_bf16_f32 v34, v39, v27
	v_cvt_pk_bf16_f32 v35, v41, v43
	v_cvt_pk_bf16_f32 v36, v45, v47
	v_cvt_pk_bf16_f32 v37, v49, v51
	v_lshl_add_u64 v[26:27], v[52:53], 0, v[2:3]
	ds_read2_b32 v[38:39], v30 offset0:16 offset1:24
	ds_read2_b32 v[40:41], v30 offset0:49 offset1:57
	ds_read2_b32 v[42:43], v30 offset0:82 offset1:90
	ds_read2_b32 v[44:45], v30 offset0:115 offset1:123
	ds_read2_b32 v[46:47], v30 offset0:148 offset1:156
	ds_read2_b32 v[48:49], v30 offset0:181 offset1:189
	ds_read2_b32 v[50:51], v30 offset0:214 offset1:222
	ds_read2_b32 v[54:55], v30 offset0:247 offset1:255
	v_or_b32_e32 v2, s2, v32
	v_mul_u32_u24_e32 v2, 0xb00, v2
	v_lshlrev_b32_e32 v2, 1, v2
	global_store_dwordx4 v[26:27], v[34:37], off
	v_lshl_add_u64 v[26:27], v[52:53], 0, v[2:3]
	v_or_b32_e32 v2, s2, v33
	v_mul_u32_u24_e32 v2, 0xb00, v2
	s_waitcnt lgkmcnt(6)
	v_cvt_pk_bf16_f32 v34, v38, v40
	s_waitcnt lgkmcnt(4)
	v_cvt_pk_bf16_f32 v35, v42, v44
	s_waitcnt lgkmcnt(2)
	v_cvt_pk_bf16_f32 v36, v46, v48
	s_waitcnt lgkmcnt(0)
	v_cvt_pk_bf16_f32 v37, v50, v54
	v_lshlrev_b32_e32 v2, 1, v2
	global_store_dwordx4 v[26:27], v[34:37], off
	v_lshl_add_u64 v[26:27], v[52:53], 0, v[2:3]
	s_mov_b64 s[2:3], 0
	v_cvt_pk_bf16_f32 v34, v39, v41
	v_cvt_pk_bf16_f32 v35, v43, v45
	v_cvt_pk_bf16_f32 v36, v47, v49
	v_cvt_pk_bf16_f32 v37, v51, v55
	global_store_dwordx4 v[26:27], v[34:37], off
	s_waitcnt lgkmcnt(0)

; #define LAS __attribute__((address_space(3)))
; __device__ __forceinline__ unsigned cvtpk(float lo, float hi) { return pg8::cvt_pk_bf16(lo, hi); }
; __device__ __forceinline__ void transpose_item(const float* W, int K, int N, int c0, int ncols, bf16_t* WT, int row_off, float scale, LAS float* scr, int item, int lane) {
;     ...
; #pragma unroll 8
;     for (int i = 0; i < 32; ++i) { const int kk = 2 * i + (lane >> 5); scr[kk * 33 + (lane & 31)] = W[(size_t)(k0 + kk) * N + c0 + n0 + (lane & 31)] * scale; }
;     asm volatile("s_waitcnt lgkmcnt(0)" ::: "memory");
;     const int c = lane & 7;
; #pragma unroll
;     for (int j = 0; j < 4; ++j) { const int n = (lane >> 3) + 8 * j; const LAS float* s = scr + (8 * c) * 33 + n;
;         u32x4 o; o.x = cvtpk(s[0 * 33], s[1 * 33]); o.y = cvtpk(s[2 * 33], s[3 * 33]); o.z = cvtpk(s[4 * 33], s[5 * 33]); o.w = cvtpk(s[6 * 33], s[7 * 33]);
;         *(u32x4*)(WT + (size_t)(row_off + n0 + n) * K + k0 + 8 * c) = o; }
;     asm volatile("s_waitcnt lgkmcnt(0)" ::: "memory");
; __device__ __forceinline__ void p0_prep(const Ptrs& P, LAS unsigned char* lds, int vcu, int G, int wave, int lane, int tid, int part) {
;     ...
;         if (r < 2816) { const int seg = r >> 6, sub = r & 63, pn = seg >> 1, bj = seg & 1;
;             transpose_item(P.w_up, 1024, 5632, bj * 2816 + 128 * pn, 128, (bf16_t*)(P.ws + WS_WUP), 256 * pn + 128 * bj, 1.f, scr, sub, lane); continue; } r -= 2816;
.LBB0_255:
	s_lshl_b32 s29, s4, 1
	s_lshl_b32 s35, s5, 1
	v_or_b32_e32 v25, s29, v5
	v_or_b32_e32 v28, s35, v2
	s_add_i32 s38, s29, 4
	s_add_i32 s39, s35, 4
	s_add_i32 s40, s29, 8
	s_add_i32 s41, s35, 8
	s_add_i32 s42, s29, 12
	s_add_i32 s43, s35, 12
	s_add_i32 s44, s29, 16
	s_add_i32 s45, s35, 16
	s_add_i32 s46, s29, 20
	s_add_i32 s47, s35, 20
	s_add_i32 s48, s29, 24
	s_add_i32 s49, s35, 24
	s_add_i32 s50, s29, 28
	s_add_i32 s51, s35, 28
	v_mad_u64_u32 v[34:35], s[36:37], v28, s33, v[26:27]
	v_mad_u64_u32 v[36:37], s[36:37], v25, s33, v[26:27]
	v_or_b32_e32 v25, s38, v5
	v_or_b32_e32 v28, s39, v2
	v_or_b32_e32 v44, s40, v5
	v_or_b32_e32 v42, s41, v2
	v_or_b32_e32 v48, s42, v5
	v_or_b32_e32 v46, s43, v2
	v_or_b32_e32 v52, s44, v5
	v_or_b32_e32 v50, s45, v2
	v_or_b32_e32 v56, s46, v5
	v_or_b32_e32 v54, s47, v2
	v_or_b32_e32 v60, s48, v5
	v_or_b32_e32 v58, s49, v2
	v_or_b32_e32 v64, s50, v5
	v_or_b32_e32 v62, s51, v2
	v_mad_u64_u32 v[38:39], s[36:37], v28, s33, v[26:27]
	v_mad_u64_u32 v[40:41], s[36:37], v25, s33, v[26:27]
	v_mad_u64_u32 v[42:43], s[36:37], v42, s33, v[26:27]
	v_mad_u64_u32 v[44:45], s[36:37], v44, s33, v[26:27]
	v_mad_u64_u32 v[46:47], s[36:37], v46, s33, v[26:27]
	v_mad_u64_u32 v[48:49], s[36:37], v48, s33, v[26:27]
	v_mad_u64_u32 v[50:51], s[36:37], v50, s33, v[26:27]
	v_mad_u64_u32 v[52:53], s[36:37], v52, s33, v[26:27]
	v_mad_u64_u32 v[54:55], s[36:37], v54, s33, v[26:27]
	v_mad_u64_u32 v[56:57], s[36:37], v56, s33, v[26:27]
	v_mad_u64_u32 v[58:59], s[36:37], v58, s33, v[26:27]
	v_mad_u64_u32 v[60:61], s[36:37], v60, s33, v[26:27]
	v_mad_u64_u32 v[62:63], s[36:37], v62, s33, v[26:27]
	v_mad_u64_u32 v[64:65], s[36:37], v64, s33, v[26:27]
	global_load_dword v25, v[34:35], off nt
	global_load_dword v28, v[36:37], off nt
	global_load_dword v66, v[38:39], off nt
	global_load_dword v67, v[40:41], off nt
	global_load_dword v68, v[42:43], off nt
	global_load_dword v69, v[44:45], off nt
	global_load_dword v70, v[46:47], off nt
	global_load_dword v71, v[48:49], off nt
	global_load_dword v72, v[50:51], off nt
	global_load_dword v73, v[52:53], off nt
	global_load_dword v74, v[54:55], off nt
	global_load_dword v75, v[56:57], off nt
	global_load_dword v76, v[58:59], off nt
	global_load_dword v77, v[60:61], off nt
	global_load_dword v78, v[62:63], off nt
	global_load_dword v79, v[64:65], off nt
	v_or_b32_e32 v36, s29, v1
	v_or_b32_e32 v34, s35, v0
	s_add_i32 s5, s5, 16
	s_add_i32 s4, s4, 16
	s_add_i32 s28, s28, -16
	v_mad_u64_u32 v[34:35], s[36:37], v34, s31, v[4:5]
	v_mad_u64_u32 v[36:37], s[36:37], v36, s31, v[4:5]
	v_or_b32_e32 v35, s38, v1
	v_or_b32_e32 v37, s39, v0
	v_or_b32_e32 v44, s40, v1
	v_or_b32_e32 v42, s41, v0
	v_or_b32_e32 v48, s42, v1
	v_or_b32_e32 v46, s43, v0
	v_or_b32_e32 v52, s44, v1
	v_or_b32_e32 v50, s45, v0
	v_or_b32_e32 v56, s46, v1
	v_or_b32_e32 v54, s47, v0
	v_or_b32_e32 v60, s48, v1
	v_or_b32_e32 v58, s49, v0
	v_or_b32_e32 v64, s50, v1
	v_or_b32_e32 v62, s51, v0
	s_cmp_lg_u32 s28, 0
	v_mad_u64_u32 v[38:39], s[36:37], v37, s31, v[4:5]
	v_mad_u64_u32 v[40:41], s[36:37], v35, s31, v[4:5]
	v_mad_u64_u32 v[42:43], s[36:37], v42, s31, v[4:5]
	v_mad_u64_u32 v[44:45], s[36:37], v44, s31, v[4:5]
	v_mad_u64_u32 v[46:47], s[36:37], v46, s31, v[4:5]
	v_mad_u64_u32 v[48:49], s[36:37], v48, s31, v[4:5]
	v_mad_u64_u32 v[50:51], s[36:37], v50, s31, v[4:5]
	v_mad_u64_u32 v[52:53], s[36:37], v52, s31, v[4:5]
	v_mad_u64_u32 v[54:55], s[36:37], v54, s31, v[4:5]
	v_mad_u64_u32 v[56:57], s[36:37], v56, s31, v[4:5]
	v_mad_u64_u32 v[58:59], s[36:37], v58, s31, v[4:5]
	v_mad_u64_u32 v[60:61], s[36:37], v60, s31, v[4:5]
	v_mad_u64_u32 v[62:63], s[36:37], v62, s31, v[4:5]
	v_mad_u64_u32 v[64:65], s[36:37], v64, s31, v[4:5]
	s_waitcnt vmcnt(0)
	ds_write_b32 v34, v25
	ds_write_b32 v36, v28
	ds_write_b32 v38, v66
	ds_write_b32 v40, v67
	ds_write_b32 v42, v68
	ds_write_b32 v44, v69
	ds_write_b32 v46, v70
	ds_write_b32 v48, v71
	ds_write_b32 v50, v72
	ds_write_b32 v52, v73
	ds_write_b32 v54, v74
	ds_write_b32 v56, v75
	ds_write_b32 v58, v76
	ds_write_b32 v60, v77
	ds_write_b32 v62, v78
	ds_write_b32 v64, v79
	s_cbranch_scc1 .LBB0_255
	s_lshl_b32 s4, s34, 1
	s_lshl_b32 s0, s0, 7
	s_and_b32 s4, s4, 0xffffff00
	s_waitcnt lgkmcnt(0)
	s_or_b32 s0, s0, s4
	ds_read2_b32 v[26:27], v30 offset0:33 offset1:41
	ds_read2_b32 v[38:39], v30 offset1:8
	ds_read2_b32 v[40:41], v30 offset0:66 offset1:74
	ds_read2_b32 v[42:43], v30 offset0:99 offset1:107
	ds_read2_b32 v[44:45], v30 offset0:132 offset1:140
	ds_read2_b32 v[46:47], v30 offset0:165 offset1:173
	ds_read2_b32 v[48:49], v30 offset0:198 offset1:206
	ds_read2_b32 v[50:51], v30 offset0:231 offset1:239
	s_or_b32 s3, s0, s3
	v_or_b32_e32 v54, s3, v29
	s_lshl_b32 s0, s2, 1
	v_ashrrev_i32_e32 v55, 31, v54
	v_lshl_add_u64 v[52:53], v[22:23], 0, s[0:1]
	v_lshlrev_b64 v[54:55], 11, v[54:55]
	s_waitcnt lgkmcnt(6)
	v_cvt_pk_bf16_f32 v34, v38, v26
	s_waitcnt lgkmcnt(4)
	v_cvt_pk_bf16_f32 v35, v40, v42
	s_waitcnt lgkmcnt(2)
	v_cvt_pk_bf16_f32 v36, v44, v46
	s_waitcnt lgkmcnt(0)
	v_cvt_pk_bf16_f32 v37, v48, v50
	v_lshl_add_u64 v[54:55], v[52:53], 0, v[54:55]
	v_or_b32_e32 v26, s3, v31
	global_store_dwordx4 v[54:55], v[34:37], off
	s_nop 1
	v_cvt_pk_bf16_f32 v34, v39, v27
	v_ashrrev_i32_e32 v27, 31, v26
	v_cvt_pk_bf16_f32 v35, v41, v43
	v_cvt_pk_bf16_f32 v36, v45, v47
	v_cvt_pk_bf16_f32 v37, v49, v51
	v_lshlrev_b64 v[26:27], 11, v[26:27]
	ds_read2_b32 v[38:39], v30 offset0:49 offset1:57
	ds_read2_b32 v[40:41], v30 offset0:16 offset1:24
	ds_read2_b32 v[42:43], v30 offset0:82 offset1:90
	ds_read2_b32 v[44:45], v30 offset0:115 offset1:123
	ds_read2_b32 v[46:47], v30 offset0:148 offset1:156
	ds_read2_b32 v[48:49], v30 offset0:181 offset1:189
	ds_read2_b32 v[50:51], v30 offset0:214 offset1:222
	ds_read2_b32 v[54:55], v30 offset0:247 offset1:255
	v_lshl_add_u64 v[26:27], v[52:53], 0, v[26:27]
	global_store_dwordx4 v[26:27], v[34:37], off
	v_or_b32_e32 v26, s3, v32
	v_ashrrev_i32_e32 v27, 31, v26
	v_lshlrev_b64 v[26:27], 11, v[26:27]
	s_waitcnt lgkmcnt(6)
	v_cvt_pk_bf16_f32 v34, v40, v38
	s_waitcnt lgkmcnt(4)
	v_cvt_pk_bf16_f32 v35, v42, v44
	s_waitcnt lgkmcnt(2)
	v_cvt_pk_bf16_f32 v36, v46, v48
	s_waitcnt lgkmcnt(0)
	v_cvt_pk_bf16_f32 v37, v50, v54
	v_lshl_add_u64 v[26:27], v[52:53], 0, v[26:27]
	global_store_dwordx4 v[26:27], v[34:37], off
	v_or_b32_e32 v26, s3, v33
	v_ashrrev_i32_e32 v27, 31, v26
	v_lshlrev_b64 v[26:27], 11, v[26:27]
	v_cvt_pk_bf16_f32 v34, v41, v39
	v_cvt_pk_bf16_f32 v35, v43, v45
	v_cvt_pk_bf16_f32 v36, v47, v49
	v_cvt_pk_bf16_f32 v37, v51, v55
	v_lshl_add_u64 v[26:27], v[52:53], 0, v[26:27]
	global_store_dwordx4 v[26:27], v[34:37], off
	s_waitcnt lgkmcnt(0)
	s_branch .LBB0_227
